# GEMM units (G1, G2, G3): first K-iteration peeled with inline-constant-0 accumulator input on the 32 first-touch MFMAs; the 128-register accumulator zeroing per unit is gone
# speedup vs baseline: 1.0082x; 1.0059x over previous
.LBB0_490:
	v_mov_b64_e32 v[2:3], s[26:27]
	s_ashr_i32 s41, s40, 31
	v_cmp_lt_i64_e32 vcc, s[16:17], v[2:3]
	s_lshl_b64 s[16:17], s[40:41], 19
	s_add_u32 s44, s46, s16
	s_addc_u32 s45, s47, s17
	s_and_b64 s[16:17], vcc, exec
	s_cselect_b32 s9, s45, s13
	s_cselect_b32 s11, s44, s12
	s_ashr_i32 s39, s38, 31
	s_lshl_b64 s[16:17], s[38:39], 19
	s_add_u32 s54, s71, s16
	s_addc_u32 s55, s73, s17
	s_and_b64 s[16:17], vcc, exec
	s_cselect_b32 s39, s55, s15
	s_cselect_b32 s41, s54, s14
	s_add_u32 s12, s12, 0x40080
	s_addc_u32 s13, s13, 0
	s_add_u32 s62, s14, 0x100
	s_addc_u32 s63, s15, 0
	s_mov_b32 s64, -2
	s_add_u32 s14, s12, 0xfffc0080
	s_addc_u32 s15, s13, -1
	s_add_i32 s65, 0, 0x10000
	v_add_u32_e32 v0, s65, v230
	ds_read_b128 v[2:5], v0
	ds_read_b128 v[6:9], v0 offset:1024
	ds_read_b128 v[10:13], v0 offset:2048
	ds_read_b128 v[14:17], v0 offset:3072
	s_cmp_eq_u32 s64, 12
	s_cselect_b32 s17, s9, s15
	s_cselect_b32 s16, s11, s14
	s_cselect_b32 s15, s39, s63
	s_cselect_b32 s14, s41, s62
	v_lshl_add_u64 v[50:51], s[12:13], 0, v[214:215]
	s_add_i32 m0, s23, 0xc000
	ds_read_b128 v[18:21], v232
	ds_read_b128 v[22:25], v232 offset:1024
	ds_read_b128 v[26:29], v232 offset:2048
	ds_read_b128 v[30:33], v232 offset:3072
	ds_read_b128 v[34:37], v232 offset:4096
	ds_read_b128 v[38:41], v232 offset:5120
	ds_read_b128 v[42:45], v232 offset:6144
	ds_read_b128 v[46:49], v232 offset:7168
	global_load_lds_dwordx4 v[50:51], off
	v_lshl_add_u64 v[50:51], s[12:13], 0, v[216:217]
	s_add_i32 m0, s23, 0xe000
	s_nop 0
	global_load_lds_dwordx4 v[50:51], off
	s_waitcnt lgkmcnt(8)
	s_barrier
	s_waitcnt lgkmcnt(0)
	s_setprio 1
	s_waitcnt lgkmcnt(0)
	v_mfma_f32_16x16x32_bf16 v[158:161], v[2:5], v[34:37], 0
	v_mfma_f32_16x16x32_bf16 v[154:157], v[10:13], v[34:37], 0
	v_mfma_f32_16x16x32_bf16 v[138:141], v[2:5], v[42:45], 0
	v_mfma_f32_16x16x32_bf16 v[134:137], v[10:13], v[42:45], 0
	v_mfma_f32_16x16x32_bf16 v[50:53], v[2:5], v[18:21], 0
	v_mfma_f32_16x16x32_bf16 v[54:57], v[10:13], v[18:21], 0
	v_mfma_f32_16x16x32_bf16 v[58:61], v[2:5], v[26:29], 0
	v_mfma_f32_16x16x32_bf16 v[150:153], v[10:13], v[26:29], 0
	v_mfma_f32_16x16x32_bf16 v[158:161], v[6:9], v[38:41], v[158:161]
	v_mfma_f32_16x16x32_bf16 v[154:157], v[14:17], v[38:41], v[154:157]
	v_mfma_f32_16x16x32_bf16 v[138:141], v[6:9], v[46:49], v[138:141]
	v_mfma_f32_16x16x32_bf16 v[134:137], v[14:17], v[46:49], v[134:137]
	v_mfma_f32_16x16x32_bf16 v[50:53], v[6:9], v[22:25], v[50:53]
	v_mfma_f32_16x16x32_bf16 v[54:57], v[14:17], v[22:25], v[54:57]
	v_mfma_f32_16x16x32_bf16 v[58:61], v[6:9], v[30:33], v[58:61]
	v_mfma_f32_16x16x32_bf16 v[150:153], v[14:17], v[30:33], v[150:153]
	s_setprio 0
	s_barrier
	s_add_i32 s86, 0, 0x14000
	s_add_i32 s65, s65, s22
	v_add_u32_e32 v0, s86, v230
	v_lshl_add_u64 v[222:223], s[14:15], 0, v[208:209]
	s_mov_b32 m0, s65
	ds_read_b128 v[162:165], v0
	ds_read_b128 v[174:177], v0 offset:1024
	ds_read_b128 v[178:181], v0 offset:2048
	ds_read_b128 v[182:185], v0 offset:3072
	global_load_lds_dwordx4 v[222:223], off
	v_lshl_add_u64 v[226:227], s[14:15], 0, v[212:213]
	s_add_i32 m0, s65, 0x2000
	s_nop 0
	global_load_lds_dwordx4 v[226:227], off
	s_barrier
	s_waitcnt lgkmcnt(0)
	s_setprio 1
	s_waitcnt lgkmcnt(0)
	v_mfma_f32_16x16x32_bf16 v[186:189], v[162:165], v[18:21], 0
	v_mfma_f32_16x16x32_bf16 v[18:21], v[178:181], v[18:21], 0
	v_mfma_f32_16x16x32_bf16 v[186:189], v[174:177], v[22:25], v[186:189]
	v_mfma_f32_16x16x32_bf16 v[18:21], v[182:185], v[22:25], v[18:21]
	v_mfma_f32_16x16x32_bf16 v[22:25], v[162:165], v[26:29], 0
	v_mfma_f32_16x16x32_bf16 v[26:29], v[178:181], v[26:29], 0
	v_mfma_f32_16x16x32_bf16 v[22:25], v[174:177], v[30:33], v[22:25]
	v_mfma_f32_16x16x32_bf16 v[26:29], v[182:185], v[30:33], v[26:29]
	v_mfma_f32_16x16x32_bf16 v[30:33], v[162:165], v[34:37], 0
	v_mfma_f32_16x16x32_bf16 v[34:37], v[178:181], v[34:37], 0
	v_mfma_f32_16x16x32_bf16 v[30:33], v[174:177], v[38:41], v[30:33]
	v_mfma_f32_16x16x32_bf16 v[34:37], v[182:185], v[38:41], v[34:37]
	v_mfma_f32_16x16x32_bf16 v[38:41], v[162:165], v[42:45], 0
	v_mfma_f32_16x16x32_bf16 v[42:45], v[178:181], v[42:45], 0
	v_mfma_f32_16x16x32_bf16 v[38:41], v[174:177], v[46:49], v[38:41]
	v_mfma_f32_16x16x32_bf16 v[42:45], v[182:185], v[46:49], v[42:45]
	s_setprio 0
	s_mov_b32 m0, s23
	v_lshl_add_u64 v[238:239], s[16:17], 0, v[206:207]
	s_barrier
	ds_read_b128 v[46:49], v232 offset:16384
	ds_read_b128 v[126:129], v232 offset:17408
	ds_read_b128 v[130:133], v232 offset:18432
	ds_read_b128 v[142:145], v232 offset:19456
	ds_read_b128 v[146:149], v232 offset:20480
	ds_read_b128 v[166:169], v232 offset:21504
	ds_read_b128 v[170:173], v232 offset:22528
	ds_read_b128 v[190:193], v232 offset:23552
	global_load_lds_dwordx4 v[238:239], off
	v_lshl_add_u64 v[240:241], s[16:17], 0, v[210:211]
	s_mov_b32 m0, s72
	s_nop 0
	global_load_lds_dwordx4 v[240:241], off
	s_barrier
	s_waitcnt lgkmcnt(0)
	s_setprio 1
	s_waitcnt lgkmcnt(0)
	v_mfma_f32_16x16x32_bf16 v[122:125], v[2:5], v[46:49], 0
	v_mfma_f32_16x16x32_bf16 v[118:121], v[10:13], v[46:49], 0
	v_mfma_f32_16x16x32_bf16 v[106:109], v[2:5], v[130:133], 0
	v_mfma_f32_16x16x32_bf16 v[102:105], v[10:13], v[130:133], 0
	v_mfma_f32_16x16x32_bf16 v[90:93], v[2:5], v[146:149], 0
	v_mfma_f32_16x16x32_bf16 v[86:89], v[10:13], v[146:149], 0
	v_mfma_f32_16x16x32_bf16 v[2:5], v[2:5], v[170:173], 0
	v_mfma_f32_16x16x32_bf16 v[122:125], v[6:9], v[126:129], v[122:125]
	v_mfma_f32_16x16x32_bf16 v[118:121], v[14:17], v[126:129], v[118:121]
	v_mfma_f32_16x16x32_bf16 v[106:109], v[6:9], v[142:145], v[106:109]
	v_mfma_f32_16x16x32_bf16 v[102:105], v[14:17], v[142:145], v[102:105]
	v_mfma_f32_16x16x32_bf16 v[90:93], v[6:9], v[166:169], v[90:93]
	v_mfma_f32_16x16x32_bf16 v[86:89], v[14:17], v[166:169], v[86:89]
	v_mfma_f32_16x16x32_bf16 v[2:5], v[6:9], v[190:193], v[2:5]
	v_mfma_f32_16x16x32_bf16 v[6:9], v[10:13], v[170:173], 0
	v_mfma_f32_16x16x32_bf16 v[6:9], v[14:17], v[190:193], v[6:9]
	s_setprio 0
	s_barrier
	s_add_u32 s66, s14, 0x40000
	s_addc_u32 s67, s15, 0
	s_add_i32 s65, s86, s22
	v_lshl_add_u64 v[10:11], s[66:67], 0, v[208:209]
	s_mov_b32 m0, s65
	s_nop 0
	global_load_lds_dwordx4 v[10:11], off
	v_lshl_add_u64 v[10:11], s[66:67], 0, v[212:213]
	s_add_i32 m0, s65, 0x2000
	s_nop 0
	global_load_lds_dwordx4 v[10:11], off
	s_waitcnt vmcnt(6)
	s_barrier
	s_setprio 1
	v_mfma_f32_16x16x32_bf16 v[70:73], v[178:181], v[130:133], 0
	v_mfma_f32_16x16x32_bf16 v[94:97], v[182:185], v[142:145], v[70:73]
	v_mfma_f32_16x16x32_bf16 v[70:73], v[162:165], v[146:149], 0
	v_mfma_f32_16x16x32_bf16 v[82:85], v[174:177], v[166:169], v[70:73]
	v_mfma_f32_16x16x32_bf16 v[70:73], v[178:181], v[146:149], 0
	v_mfma_f32_16x16x32_bf16 v[66:69], v[162:165], v[170:173], 0
	v_mfma_f32_16x16x32_bf16 v[62:65], v[178:181], v[170:173], 0
	v_mfma_f32_16x16x32_bf16 v[10:13], v[162:165], v[46:49], 0
	v_mfma_f32_16x16x32_bf16 v[14:17], v[178:181], v[46:49], 0
	v_mfma_f32_16x16x32_bf16 v[46:49], v[162:165], v[130:133], 0
	v_mfma_f32_16x16x32_bf16 v[78:81], v[182:185], v[166:169], v[70:73]
	v_mfma_f32_16x16x32_bf16 v[66:69], v[174:177], v[190:193], v[66:69]
	v_mfma_f32_16x16x32_bf16 v[62:65], v[182:185], v[190:193], v[62:65]
	v_mfma_f32_16x16x32_bf16 v[10:13], v[174:177], v[126:129], v[10:13]
	v_mfma_f32_16x16x32_bf16 v[14:17], v[182:185], v[126:129], v[14:17]
	v_mfma_f32_16x16x32_bf16 v[46:49], v[174:177], v[142:145], v[46:49]
	s_setprio 0
	s_add_i32 s65, 0, 0x18000
	v_add_u32_e32 v0, s65, v230
	s_barrier
	ds_read_b128 v[70:73], v0
	ds_read_b128 v[74:77], v0 offset:1024
	ds_read_b128 v[98:101], v0 offset:2048
	ds_read_b128 v[110:113], v0 offset:3072
	s_add_u32 s16, s16, 0x40000
	s_addc_u32 s17, s17, 0
	s_mov_b32 m0, s83
	v_lshl_add_u64 v[146:147], s[16:17], 0, v[206:207]
	ds_read_b128 v[114:117], v232 offset:32768
	ds_read_b128 v[126:129], v232 offset:33792
	ds_read_b128 v[130:133], v232 offset:34816
	ds_read_b128 v[142:145], v232 offset:35840
	ds_read_b128 v[162:165], v232 offset:36864
	ds_read_b128 v[174:177], v232 offset:37888
	ds_read_b128 v[218:221], v232 offset:38912
	ds_read_b128 v[234:237], v232 offset:39936
	global_load_lds_dwordx4 v[146:147], off
	v_lshl_add_u64 v[146:147], s[16:17], 0, v[210:211]
	s_mov_b32 m0, s84
	s_nop 0
	global_load_lds_dwordx4 v[146:147], off
	s_waitcnt lgkmcnt(8)
	s_barrier
	s_waitcnt lgkmcnt(0)
	s_setprio 1
	s_waitcnt lgkmcnt(0)
	v_mfma_f32_16x16x32_bf16 v[50:53], v[70:73], v[114:117], v[50:53]
	v_mfma_f32_16x16x32_bf16 v[202:205], v[74:77], v[126:129], v[50:53]
	v_mfma_f32_16x16x32_bf16 v[50:53], v[98:101], v[114:117], v[54:57]
	v_mfma_f32_16x16x32_bf16 v[198:201], v[110:113], v[126:129], v[50:53]
	v_mfma_f32_16x16x32_bf16 v[50:53], v[70:73], v[130:133], v[58:61]
	v_mfma_f32_16x16x32_bf16 v[182:185], v[74:77], v[142:145], v[50:53]
	v_mfma_f32_16x16x32_bf16 v[50:53], v[98:101], v[130:133], v[150:153]
	v_mfma_f32_16x16x32_bf16 v[178:181], v[110:113], v[142:145], v[50:53]
	v_mfma_f32_16x16x32_bf16 v[50:53], v[70:73], v[162:165], v[158:161]
	v_mfma_f32_16x16x32_bf16 v[158:161], v[74:77], v[174:177], v[50:53]
	v_mfma_f32_16x16x32_bf16 v[50:53], v[98:101], v[162:165], v[154:157]
	v_mfma_f32_16x16x32_bf16 v[154:157], v[110:113], v[174:177], v[50:53]
	v_mfma_f32_16x16x32_bf16 v[50:53], v[70:73], v[218:221], v[138:141]
	v_mfma_f32_16x16x32_bf16 v[138:141], v[74:77], v[234:237], v[50:53]
	v_mfma_f32_16x16x32_bf16 v[50:53], v[98:101], v[218:221], v[134:137]
	v_mfma_f32_16x16x32_bf16 v[134:137], v[110:113], v[234:237], v[50:53]
	s_setprio 0
	s_barrier
	s_add_i32 s16, 0, 0x1c000
	s_add_i32 s17, s65, s22
	v_add_u32_e32 v0, s16, v230
	v_lshl_add_u64 v[146:147], v[222:223], 0, s[20:21]
	s_mov_b32 m0, s17
	ds_read_b128 v[50:53], v0
	ds_read_b128 v[54:57], v0 offset:1024
	ds_read_b128 v[58:61], v0 offset:2048
	ds_read_b128 v[150:153], v0 offset:3072
	global_load_lds_dwordx4 v[146:147], off
	v_lshl_add_u64 v[146:147], v[226:227], 0, s[20:21]
	s_add_i32 m0, s17, 0x2000
	s_nop 0
	global_load_lds_dwordx4 v[146:147], off
	s_barrier
	s_waitcnt lgkmcnt(0)
	s_setprio 1
	s_waitcnt lgkmcnt(0)
	v_mfma_f32_16x16x32_bf16 v[18:21], v[58:61], v[114:117], v[18:21]
	v_mfma_f32_16x16x32_bf16 v[190:193], v[150:153], v[126:129], v[18:21]
	v_mfma_f32_16x16x32_bf16 v[18:21], v[50:53], v[130:133], v[22:25]
	v_mfma_f32_16x16x32_bf16 v[170:173], v[54:57], v[142:145], v[18:21]
	v_mfma_f32_16x16x32_bf16 v[18:21], v[58:61], v[130:133], v[26:29]
	v_mfma_f32_16x16x32_bf16 v[146:149], v[50:53], v[114:117], v[186:189]
	v_mfma_f32_16x16x32_bf16 v[166:169], v[150:153], v[142:145], v[18:21]
	v_mfma_f32_16x16x32_bf16 v[18:21], v[50:53], v[162:165], v[30:33]
	v_mfma_f32_16x16x32_bf16 v[194:197], v[54:57], v[126:129], v[146:149]
	v_mfma_f32_16x16x32_bf16 v[146:149], v[54:57], v[174:177], v[18:21]
	v_mfma_f32_16x16x32_bf16 v[18:21], v[58:61], v[162:165], v[34:37]
	v_mfma_f32_16x16x32_bf16 v[142:145], v[150:153], v[174:177], v[18:21]
	v_mfma_f32_16x16x32_bf16 v[18:21], v[50:53], v[218:221], v[38:41]
	v_mfma_f32_16x16x32_bf16 v[130:133], v[54:57], v[234:237], v[18:21]
	v_mfma_f32_16x16x32_bf16 v[18:21], v[58:61], v[218:221], v[42:45]
	v_mfma_f32_16x16x32_bf16 v[126:129], v[150:153], v[234:237], v[18:21]
	s_setprio 0
	s_mov_b32 m0, s91
	v_lshl_add_u64 v[114:115], v[238:239], 0, s[20:21]
	s_barrier
	s_nop 2
	ds_read_b128 v[18:21], v232 offset:49152
	ds_read_b128 v[22:25], v232 offset:50176
	ds_read_b128 v[26:29], v232 offset:51200
	ds_read_b128 v[30:33], v232 offset:52224
	ds_read_b128 v[34:37], v232 offset:53248
	ds_read_b128 v[38:41], v232 offset:54272
	ds_read_b128 v[42:45], v232 offset:55296
	ds_read_b128 v[162:165], v232 offset:56320
	global_load_lds_dwordx4 v[114:115], off
	v_lshl_add_u64 v[114:115], v[240:241], 0, s[20:21]
	s_mov_b32 m0, s59
	s_nop 0
	global_load_lds_dwordx4 v[114:115], off
	s_barrier
	s_waitcnt lgkmcnt(0)
	s_setprio 1
	s_waitcnt lgkmcnt(0)
	v_mfma_f32_16x16x32_bf16 v[114:117], v[70:73], v[18:21], v[122:125]
	v_mfma_f32_16x16x32_bf16 v[106:109], v[70:73], v[26:29], v[106:109]
	v_mfma_f32_16x16x32_bf16 v[90:93], v[70:73], v[34:37], v[90:93]
	v_mfma_f32_16x16x32_bf16 v[2:5], v[70:73], v[42:45], v[2:5]
	v_mfma_f32_16x16x32_bf16 v[122:125], v[74:77], v[22:25], v[114:117]
	v_mfma_f32_16x16x32_bf16 v[114:117], v[98:101], v[18:21], v[118:121]
	v_mfma_f32_16x16x32_bf16 v[106:109], v[74:77], v[30:33], v[106:109]
	v_mfma_f32_16x16x32_bf16 v[102:105], v[98:101], v[26:29], v[102:105]
	v_mfma_f32_16x16x32_bf16 v[90:93], v[74:77], v[38:41], v[90:93]
	v_mfma_f32_16x16x32_bf16 v[86:89], v[98:101], v[34:37], v[86:89]
	v_mfma_f32_16x16x32_bf16 v[74:77], v[74:77], v[162:165], v[2:5]
	v_mfma_f32_16x16x32_bf16 v[2:5], v[98:101], v[42:45], v[6:9]
	v_mfma_f32_16x16x32_bf16 v[118:121], v[110:113], v[22:25], v[114:117]
	v_mfma_f32_16x16x32_bf16 v[102:105], v[110:113], v[30:33], v[102:105]
	v_mfma_f32_16x16x32_bf16 v[86:89], v[110:113], v[38:41], v[86:89]
	v_mfma_f32_16x16x32_bf16 v[70:73], v[110:113], v[162:165], v[2:5]
	s_setprio 0
	s_barrier
	s_add_u32 s14, s14, 0x40080
	s_addc_u32 s15, s15, 0
	s_add_i32 s16, s16, s22
	v_lshl_add_u64 v[2:3], s[14:15], 0, v[208:209]
	s_mov_b32 m0, s16
	s_nop 0
	global_load_lds_dwordx4 v[2:3], off
	v_lshl_add_u64 v[2:3], s[14:15], 0, v[212:213]
	s_add_i32 m0, s16, 0x2000
	s_nop 0
	global_load_lds_dwordx4 v[2:3], off
	s_waitcnt vmcnt(6)
	s_barrier
	s_setprio 1
	v_mfma_f32_16x16x32_bf16 v[2:5], v[50:53], v[18:21], v[10:13]
	v_mfma_f32_16x16x32_bf16 v[114:117], v[54:57], v[22:25], v[2:5]
	v_mfma_f32_16x16x32_bf16 v[2:5], v[58:61], v[18:21], v[14:17]
	v_mfma_f32_16x16x32_bf16 v[110:113], v[150:153], v[22:25], v[2:5]
	v_mfma_f32_16x16x32_bf16 v[2:5], v[50:53], v[26:29], v[46:49]
	v_mfma_f32_16x16x32_bf16 v[98:101], v[54:57], v[30:33], v[2:5]
	v_mfma_f32_16x16x32_bf16 v[2:5], v[58:61], v[26:29], v[94:97]
	v_mfma_f32_16x16x32_bf16 v[94:97], v[150:153], v[30:33], v[2:5]
	v_mfma_f32_16x16x32_bf16 v[2:5], v[50:53], v[34:37], v[82:85]
	v_mfma_f32_16x16x32_bf16 v[82:85], v[54:57], v[38:41], v[2:5]
	v_mfma_f32_16x16x32_bf16 v[2:5], v[58:61], v[34:37], v[78:81]
	v_mfma_f32_16x16x32_bf16 v[78:81], v[150:153], v[38:41], v[2:5]
	v_mfma_f32_16x16x32_bf16 v[2:5], v[50:53], v[42:45], v[66:69]
	v_mfma_f32_16x16x32_bf16 v[66:69], v[54:57], v[162:165], v[2:5]
	v_mfma_f32_16x16x32_bf16 v[2:5], v[58:61], v[42:45], v[62:65]
	v_mfma_f32_16x16x32_bf16 v[62:65], v[150:153], v[162:165], v[2:5]
	s_setprio 0
	s_add_i32 s64, s64, 2
	s_add_u32 s12, s12, 0x100
	s_addc_u32 s13, s13, 0
	s_add_u32 s62, s62, 0x100
	s_addc_u32 s63, s63, 0
	s_cmp_gt_u32 s64, 13
	s_barrier
	s_cbranch_scc0 .LBB0_491
	s_branch .Lpeel_exit_g1

.Lpeel_exit_g1:
	s_lshl_b32 s9, s10, 8
	v_readlane_b32 s10, v255, 26
	v_readlane_b32 s11, v255, 27
	s_mov_b32 s86, -1
	s_andn2_b64 vcc, exec, s[10:11]
	s_mov_b32 s62, -1
	s_cbranch_vccnz .LBB0_494
	s_add_i32 s10, s9, 0xfffff900
	s_lshr_b32 s11, s10, 5
	s_or_b32 s11, s11, s85
	s_cmpk_lt_u32 s10, 0x280
	s_cselect_b32 s86, s11, -1
	s_add_i32 s10, s9, 0xfffff980
	s_lshr_b32 s11, s10, 5
	s_or_b32 s11, s11, s85
	s_cmpk_lt_u32 s10, 0x280
	s_cselect_b32 s62, s11, -1

.LBB0_860:
	s_add_u32 vcc_lo, s12, 0x100
	s_addc_u32 vcc_hi, s13, 0
	s_mov_b32 s8, 0
	s_add_i32 s63, s8, 2
	s_add_u32 s6, s10, 0x100
	s_addc_u32 s7, s11, 0
	s_add_i32 s77, 0, 0x10000
	v_add_u32_e32 v0, s77, v234
	ds_read_b128 v[2:5], v0
	ds_read_b128 v[6:9], v0 offset:1024
	ds_read_b128 v[10:13], v0 offset:2048
	ds_read_b128 v[14:17], v0 offset:3072
	s_cmp_eq_u32 s23, s8
	s_cselect_b32 s8, s38, s6
	s_cselect_b32 s9, s39, s7
	s_cselect_b32 s13, s41, vcc_hi
	s_cselect_b32 s12, s40, vcc_lo
	v_lshl_add_u64 v[50:51], s[10:11], 0, v[214:215]
	s_add_i32 m0, s56, 0xc000
	ds_read_b128 v[18:21], v237
	ds_read_b128 v[22:25], v237 offset:1024
	ds_read_b128 v[26:29], v237 offset:2048
	ds_read_b128 v[30:33], v237 offset:3072
	ds_read_b128 v[34:37], v237 offset:4096
	ds_read_b128 v[38:41], v237 offset:5120
	ds_read_b128 v[42:45], v237 offset:6144
	ds_read_b128 v[46:49], v237 offset:7168
	global_load_lds_dwordx4 v[50:51], off
	v_lshl_add_u64 v[50:51], s[10:11], 0, v[216:217]
	s_add_i32 m0, s56, 0xe000
	s_nop 0
	global_load_lds_dwordx4 v[50:51], off
	s_waitcnt lgkmcnt(8)
	s_barrier
	s_waitcnt lgkmcnt(0)
	s_setprio 1
	s_waitcnt lgkmcnt(0)
	v_mfma_f32_16x16x32_bf16 v[154:157], v[2:5], v[34:37], 0
	v_mfma_f32_16x16x32_bf16 v[150:153], v[10:13], v[34:37], 0
	v_mfma_f32_16x16x32_bf16 v[138:141], v[2:5], v[42:45], 0
	v_mfma_f32_16x16x32_bf16 v[134:137], v[10:13], v[42:45], 0
	v_mfma_f32_16x16x32_bf16 v[50:53], v[2:5], v[18:21], 0
	v_mfma_f32_16x16x32_bf16 v[54:57], v[10:13], v[18:21], 0
	v_mfma_f32_16x16x32_bf16 v[58:61], v[2:5], v[26:29], 0
	v_mfma_f32_16x16x32_bf16 v[166:169], v[10:13], v[26:29], 0
	v_mfma_f32_16x16x32_bf16 v[154:157], v[6:9], v[38:41], v[154:157]
	v_mfma_f32_16x16x32_bf16 v[150:153], v[14:17], v[38:41], v[150:153]
	v_mfma_f32_16x16x32_bf16 v[138:141], v[6:9], v[46:49], v[138:141]
	v_mfma_f32_16x16x32_bf16 v[134:137], v[14:17], v[46:49], v[134:137]
	v_mfma_f32_16x16x32_bf16 v[50:53], v[6:9], v[22:25], v[50:53]
	v_mfma_f32_16x16x32_bf16 v[54:57], v[14:17], v[22:25], v[54:57]
	v_mfma_f32_16x16x32_bf16 v[58:61], v[6:9], v[30:33], v[58:61]
	v_mfma_f32_16x16x32_bf16 v[166:169], v[14:17], v[30:33], v[166:169]
	s_setprio 0
	s_barrier
	s_add_i32 s80, 0, 0x14000
	s_add_i32 s10, s77, s53
	v_add_u32_e32 v0, s80, v234
	v_lshl_add_u64 v[222:223], s[12:13], 0, v[208:209]
	s_mov_b32 m0, s10
	ds_read_b128 v[170:173], v0
	ds_read_b128 v[174:177], v0 offset:1024
	ds_read_b128 v[178:181], v0 offset:2048
	ds_read_b128 v[190:193], v0 offset:3072
	global_load_lds_dwordx4 v[222:223], off
	v_lshl_add_u64 v[226:227], s[12:13], 0, v[212:213]
	s_add_i32 m0, s10, 0x2000
	s_nop 0
	global_load_lds_dwordx4 v[226:227], off
	s_barrier
	s_waitcnt lgkmcnt(0)
	s_setprio 1
	s_waitcnt lgkmcnt(0)
	v_mfma_f32_16x16x32_bf16 v[186:189], v[170:173], v[18:21], 0
	v_mfma_f32_16x16x32_bf16 v[18:21], v[178:181], v[18:21], 0
	v_mfma_f32_16x16x32_bf16 v[186:189], v[174:177], v[22:25], v[186:189]
	v_mfma_f32_16x16x32_bf16 v[18:21], v[190:193], v[22:25], v[18:21]
	v_mfma_f32_16x16x32_bf16 v[22:25], v[170:173], v[26:29], 0
	v_mfma_f32_16x16x32_bf16 v[26:29], v[178:181], v[26:29], 0
	v_mfma_f32_16x16x32_bf16 v[22:25], v[174:177], v[30:33], v[22:25]
	v_mfma_f32_16x16x32_bf16 v[26:29], v[190:193], v[30:33], v[26:29]
	v_mfma_f32_16x16x32_bf16 v[30:33], v[170:173], v[34:37], 0
	v_mfma_f32_16x16x32_bf16 v[34:37], v[178:181], v[34:37], 0
	v_mfma_f32_16x16x32_bf16 v[30:33], v[174:177], v[38:41], v[30:33]
	v_mfma_f32_16x16x32_bf16 v[34:37], v[190:193], v[38:41], v[34:37]
	v_mfma_f32_16x16x32_bf16 v[38:41], v[170:173], v[42:45], 0
	v_mfma_f32_16x16x32_bf16 v[42:45], v[178:181], v[42:45], 0
	v_mfma_f32_16x16x32_bf16 v[38:41], v[174:177], v[46:49], v[38:41]
	v_mfma_f32_16x16x32_bf16 v[42:45], v[190:193], v[46:49], v[42:45]
	s_setprio 0
	s_mov_b32 m0, s56
	v_lshl_add_u64 v[228:229], s[8:9], 0, v[206:207]
	s_barrier
	ds_read_b128 v[46:49], v237 offset:16384
	ds_read_b128 v[126:129], v237 offset:17408
	ds_read_b128 v[130:133], v237 offset:18432
	ds_read_b128 v[142:145], v237 offset:19456
	ds_read_b128 v[146:149], v237 offset:20480
	ds_read_b128 v[158:161], v237 offset:21504
	ds_read_b128 v[162:165], v237 offset:22528
	ds_read_b128 v[182:185], v237 offset:23552
	global_load_lds_dwordx4 v[228:229], off
	v_lshl_add_u64 v[230:231], s[8:9], 0, v[210:211]
	s_mov_b32 m0, s57
	s_nop 0
	global_load_lds_dwordx4 v[230:231], off
	s_barrier
	s_waitcnt lgkmcnt(0)
	s_setprio 1
	s_waitcnt lgkmcnt(0)
	v_mfma_f32_16x16x32_bf16 v[122:125], v[2:5], v[46:49], 0
	v_mfma_f32_16x16x32_bf16 v[118:121], v[10:13], v[46:49], 0
	v_mfma_f32_16x16x32_bf16 v[110:113], v[2:5], v[130:133], 0
	v_mfma_f32_16x16x32_bf16 v[102:105], v[10:13], v[130:133], 0
	v_mfma_f32_16x16x32_bf16 v[94:97], v[2:5], v[146:149], 0
	v_mfma_f32_16x16x32_bf16 v[86:89], v[10:13], v[146:149], 0
	v_mfma_f32_16x16x32_bf16 v[2:5], v[2:5], v[162:165], 0
	v_mfma_f32_16x16x32_bf16 v[122:125], v[6:9], v[126:129], v[122:125]
	v_mfma_f32_16x16x32_bf16 v[118:121], v[14:17], v[126:129], v[118:121]
	v_mfma_f32_16x16x32_bf16 v[110:113], v[6:9], v[142:145], v[110:113]
	v_mfma_f32_16x16x32_bf16 v[102:105], v[14:17], v[142:145], v[102:105]
	v_mfma_f32_16x16x32_bf16 v[94:97], v[6:9], v[158:161], v[94:97]
	v_mfma_f32_16x16x32_bf16 v[86:89], v[14:17], v[158:161], v[86:89]
	v_mfma_f32_16x16x32_bf16 v[2:5], v[6:9], v[182:185], v[2:5]
	v_mfma_f32_16x16x32_bf16 v[6:9], v[10:13], v[162:165], 0
	v_mfma_f32_16x16x32_bf16 v[6:9], v[14:17], v[182:185], v[6:9]
	s_setprio 0
	s_barrier
	s_add_u32 s10, s12, s73
	s_addc_u32 s11, s13, 0
	s_add_i32 s12, s80, s53
	v_lshl_add_u64 v[238:239], s[10:11], 0, v[208:209]
	s_mov_b32 m0, s12
	v_lshl_add_u64 v[240:241], s[10:11], 0, v[212:213]
	global_load_lds_dwordx4 v[238:239], off
	s_add_i32 m0, s12, 0x2000
	s_nop 0
	global_load_lds_dwordx4 v[240:241], off
	s_waitcnt vmcnt(6)
	s_barrier
	s_setprio 1
	v_mfma_f32_16x16x32_bf16 v[70:73], v[178:181], v[130:133], 0
	v_mfma_f32_16x16x32_bf16 v[90:93], v[190:193], v[142:145], v[70:73]
	v_mfma_f32_16x16x32_bf16 v[70:73], v[170:173], v[146:149], 0
	v_mfma_f32_16x16x32_bf16 v[82:85], v[174:177], v[158:161], v[70:73]
	v_mfma_f32_16x16x32_bf16 v[70:73], v[178:181], v[146:149], 0
	v_mfma_f32_16x16x32_bf16 v[66:69], v[170:173], v[162:165], 0
	v_mfma_f32_16x16x32_bf16 v[62:65], v[178:181], v[162:165], 0
	v_mfma_f32_16x16x32_bf16 v[10:13], v[170:173], v[46:49], 0
	v_mfma_f32_16x16x32_bf16 v[14:17], v[178:181], v[46:49], 0
	v_mfma_f32_16x16x32_bf16 v[46:49], v[170:173], v[130:133], 0
	v_mfma_f32_16x16x32_bf16 v[74:77], v[190:193], v[158:161], v[70:73]
	v_mfma_f32_16x16x32_bf16 v[66:69], v[174:177], v[182:185], v[66:69]
	v_mfma_f32_16x16x32_bf16 v[62:65], v[190:193], v[182:185], v[62:65]
	v_mfma_f32_16x16x32_bf16 v[10:13], v[174:177], v[126:129], v[10:13]
	v_mfma_f32_16x16x32_bf16 v[14:17], v[190:193], v[126:129], v[14:17]
	v_mfma_f32_16x16x32_bf16 v[46:49], v[174:177], v[142:145], v[46:49]
	s_setprio 0
	s_add_i32 s10, 0, 0x18000
	v_add_u32_e32 v0, s10, v234
	s_barrier
	ds_read_b128 v[70:73], v0
	ds_read_b128 v[78:81], v0 offset:1024
	ds_read_b128 v[98:101], v0 offset:2048
	ds_read_b128 v[106:109], v0 offset:3072
	s_add_u32 s8, s8, 0xa0000
	s_addc_u32 s9, s9, 0
	s_mov_b32 m0, s58
	v_lshl_add_u64 v[146:147], s[8:9], 0, v[206:207]
	ds_read_b128 v[114:117], v237 offset:32768
	ds_read_b128 v[126:129], v237 offset:33792
	ds_read_b128 v[130:133], v237 offset:34816
	ds_read_b128 v[142:145], v237 offset:35840
	ds_read_b128 v[174:177], v237 offset:36864
	ds_read_b128 v[190:193], v237 offset:37888
	ds_read_b128 v[194:197], v237 offset:38912
	ds_read_b128 v[218:221], v237 offset:39936
	global_load_lds_dwordx4 v[146:147], off
	v_lshl_add_u64 v[146:147], s[8:9], 0, v[210:211]
	s_mov_b32 m0, s59
	s_nop 0
	global_load_lds_dwordx4 v[146:147], off
	s_waitcnt lgkmcnt(8)
	s_barrier
	s_waitcnt lgkmcnt(0)
	s_setprio 1
	s_waitcnt lgkmcnt(0)
	v_mfma_f32_16x16x32_bf16 v[50:53], v[70:73], v[114:117], v[50:53]
	v_mfma_f32_16x16x32_bf16 v[202:205], v[78:81], v[126:129], v[50:53]
	v_mfma_f32_16x16x32_bf16 v[50:53], v[98:101], v[114:117], v[54:57]
	v_mfma_f32_16x16x32_bf16 v[198:201], v[106:109], v[126:129], v[50:53]
	v_mfma_f32_16x16x32_bf16 v[50:53], v[70:73], v[130:133], v[58:61]
	v_mfma_f32_16x16x32_bf16 v[178:181], v[78:81], v[142:145], v[50:53]
	v_mfma_f32_16x16x32_bf16 v[50:53], v[98:101], v[130:133], v[166:169]
	v_mfma_f32_16x16x32_bf16 v[170:173], v[106:109], v[142:145], v[50:53]
	v_mfma_f32_16x16x32_bf16 v[50:53], v[70:73], v[174:177], v[154:157]
	v_mfma_f32_16x16x32_bf16 v[154:157], v[78:81], v[190:193], v[50:53]
	v_mfma_f32_16x16x32_bf16 v[50:53], v[98:101], v[174:177], v[150:153]
	v_mfma_f32_16x16x32_bf16 v[150:153], v[106:109], v[190:193], v[50:53]
	v_mfma_f32_16x16x32_bf16 v[50:53], v[70:73], v[194:197], v[138:141]
	v_mfma_f32_16x16x32_bf16 v[138:141], v[78:81], v[218:221], v[50:53]
	v_mfma_f32_16x16x32_bf16 v[50:53], v[98:101], v[194:197], v[134:137]
	v_mfma_f32_16x16x32_bf16 v[134:137], v[106:109], v[218:221], v[50:53]
	s_setprio 0
	s_barrier
	s_add_i32 s8, 0, 0x1c000
	s_add_i32 s9, s10, s53
	v_add_u32_e32 v0, s8, v234
	v_lshl_add_u64 v[146:147], v[222:223], 0, s[20:21]
	s_mov_b32 m0, s9
	ds_read_b128 v[50:53], v0
	ds_read_b128 v[54:57], v0 offset:1024
	ds_read_b128 v[58:61], v0 offset:2048
	ds_read_b128 v[166:169], v0 offset:3072
	global_load_lds_dwordx4 v[146:147], off
	v_lshl_add_u64 v[146:147], v[226:227], 0, s[20:21]
	s_add_i32 m0, s9, 0x2000
	s_nop 0
	global_load_lds_dwordx4 v[146:147], off
	s_barrier
	s_waitcnt lgkmcnt(0)
	s_setprio 1
	s_waitcnt lgkmcnt(0)
	v_mfma_f32_16x16x32_bf16 v[18:21], v[58:61], v[114:117], v[18:21]
	v_mfma_f32_16x16x32_bf16 v[182:185], v[166:169], v[126:129], v[18:21]
	v_mfma_f32_16x16x32_bf16 v[18:21], v[50:53], v[130:133], v[22:25]
	v_mfma_f32_16x16x32_bf16 v[162:165], v[54:57], v[142:145], v[18:21]
	v_mfma_f32_16x16x32_bf16 v[18:21], v[58:61], v[130:133], v[26:29]
	v_mfma_f32_16x16x32_bf16 v[146:149], v[50:53], v[114:117], v[186:189]
	v_mfma_f32_16x16x32_bf16 v[158:161], v[166:169], v[142:145], v[18:21]
	v_mfma_f32_16x16x32_bf16 v[18:21], v[50:53], v[174:177], v[30:33]
	v_mfma_f32_16x16x32_bf16 v[186:189], v[54:57], v[126:129], v[146:149]
	v_mfma_f32_16x16x32_bf16 v[146:149], v[54:57], v[190:193], v[18:21]
	v_mfma_f32_16x16x32_bf16 v[18:21], v[58:61], v[174:177], v[34:37]
	v_mfma_f32_16x16x32_bf16 v[142:145], v[166:169], v[190:193], v[18:21]
	v_mfma_f32_16x16x32_bf16 v[18:21], v[50:53], v[194:197], v[38:41]
	v_mfma_f32_16x16x32_bf16 v[130:133], v[54:57], v[218:221], v[18:21]
	v_mfma_f32_16x16x32_bf16 v[18:21], v[58:61], v[194:197], v[42:45]
	v_mfma_f32_16x16x32_bf16 v[126:129], v[166:169], v[218:221], v[18:21]
	s_setprio 0
	s_mov_b32 m0, s72
	v_lshl_add_u64 v[114:115], v[228:229], 0, s[20:21]
	s_barrier
	s_nop 2
	ds_read_b128 v[18:21], v237 offset:49152
	ds_read_b128 v[22:25], v237 offset:50176
	ds_read_b128 v[26:29], v237 offset:51200
	ds_read_b128 v[30:33], v237 offset:52224
	ds_read_b128 v[34:37], v237 offset:53248
	ds_read_b128 v[38:41], v237 offset:54272
	ds_read_b128 v[42:45], v237 offset:55296
	ds_read_b128 v[174:177], v237 offset:56320
	global_load_lds_dwordx4 v[114:115], off
	v_lshl_add_u64 v[114:115], v[230:231], 0, s[20:21]
	s_mov_b32 m0, s22
	s_nop 0
	global_load_lds_dwordx4 v[114:115], off
	s_barrier
	s_waitcnt lgkmcnt(0)
	s_setprio 1
	s_waitcnt lgkmcnt(0)
	v_mfma_f32_16x16x32_bf16 v[114:117], v[70:73], v[18:21], v[122:125]
	v_mfma_f32_16x16x32_bf16 v[110:113], v[70:73], v[26:29], v[110:113]
	v_mfma_f32_16x16x32_bf16 v[94:97], v[70:73], v[34:37], v[94:97]
	v_mfma_f32_16x16x32_bf16 v[2:5], v[70:73], v[42:45], v[2:5]
	v_mfma_f32_16x16x32_bf16 v[122:125], v[78:81], v[22:25], v[114:117]
	v_mfma_f32_16x16x32_bf16 v[114:117], v[98:101], v[18:21], v[118:121]
	v_mfma_f32_16x16x32_bf16 v[110:113], v[78:81], v[30:33], v[110:113]
	v_mfma_f32_16x16x32_bf16 v[102:105], v[98:101], v[26:29], v[102:105]
	v_mfma_f32_16x16x32_bf16 v[94:97], v[78:81], v[38:41], v[94:97]
	v_mfma_f32_16x16x32_bf16 v[86:89], v[98:101], v[34:37], v[86:89]
	v_mfma_f32_16x16x32_bf16 v[78:81], v[78:81], v[174:177], v[2:5]
	v_mfma_f32_16x16x32_bf16 v[2:5], v[98:101], v[42:45], v[6:9]
	v_mfma_f32_16x16x32_bf16 v[118:121], v[106:109], v[22:25], v[114:117]
	v_mfma_f32_16x16x32_bf16 v[102:105], v[106:109], v[30:33], v[102:105]
	v_mfma_f32_16x16x32_bf16 v[86:89], v[106:109], v[38:41], v[86:89]
	v_mfma_f32_16x16x32_bf16 v[70:73], v[106:109], v[174:177], v[2:5]
	s_setprio 0
	s_barrier
	s_add_i32 s8, s8, s53
	s_nop 0
	v_lshl_add_u64 v[2:3], v[238:239], 0, s[20:21]
	s_mov_b32 m0, s8
	s_nop 0
	global_load_lds_dwordx4 v[2:3], off
	v_lshl_add_u64 v[2:3], v[240:241], 0, s[20:21]
	s_add_i32 m0, s8, 0x2000
	s_nop 0
	global_load_lds_dwordx4 v[2:3], off
	s_waitcnt vmcnt(6)
	s_barrier
	s_setprio 1
	v_mfma_f32_16x16x32_bf16 v[2:5], v[50:53], v[18:21], v[10:13]
	v_mfma_f32_16x16x32_bf16 v[114:117], v[54:57], v[22:25], v[2:5]
	v_mfma_f32_16x16x32_bf16 v[2:5], v[58:61], v[18:21], v[14:17]
	v_mfma_f32_16x16x32_bf16 v[106:109], v[166:169], v[22:25], v[2:5]
	v_mfma_f32_16x16x32_bf16 v[2:5], v[50:53], v[26:29], v[46:49]
	v_mfma_f32_16x16x32_bf16 v[98:101], v[54:57], v[30:33], v[2:5]
	v_mfma_f32_16x16x32_bf16 v[2:5], v[58:61], v[26:29], v[90:93]
	v_mfma_f32_16x16x32_bf16 v[90:93], v[166:169], v[30:33], v[2:5]
	v_mfma_f32_16x16x32_bf16 v[2:5], v[50:53], v[34:37], v[82:85]
	v_mfma_f32_16x16x32_bf16 v[82:85], v[54:57], v[38:41], v[2:5]
	v_mfma_f32_16x16x32_bf16 v[2:5], v[58:61], v[34:37], v[74:77]
	v_mfma_f32_16x16x32_bf16 v[74:77], v[166:169], v[38:41], v[2:5]
	v_mfma_f32_16x16x32_bf16 v[2:5], v[50:53], v[42:45], v[66:69]
	v_mfma_f32_16x16x32_bf16 v[66:69], v[54:57], v[174:177], v[2:5]
	v_mfma_f32_16x16x32_bf16 v[2:5], v[58:61], v[42:45], v[62:65]
	v_mfma_f32_16x16x32_bf16 v[62:65], v[166:169], v[174:177], v[2:5]
	s_setprio 0
	s_add_u32 vcc_lo, vcc_lo, 0x100
	s_addc_u32 vcc_hi, vcc_hi, 0
	s_cmp_ge_u32 s63, s91
	s_mov_b64 s[10:11], s[6:7]
	s_mov_b32 s8, s63
	s_barrier
	s_cbranch_scc0 .LBB0_861
	s_branch .Lpeel_exit_g2

.Lpeel_exit_g2:
	s_lshl_b32 s6, s45, 8
	s_or_b32 s63, s6, s71
	s_cmp_gt_i32 s45, -1
	s_cselect_b64 s[6:7], -1, 0
	s_cmp_lt_i32 s45, 0
	s_cselect_b64 s[8:9], -1, 0
	s_or_b64 s[8:9], s[16:17], s[8:9]
	s_and_b64 vcc, exec, s[8:9]
	s_cbranch_vccnz .LBB0_865
	s_lshr_b32 s8, s63, 5
	s_mul_i32 s8, s8, 0xaaaaaaab
	s_add_i32 s8, s8, 0xaaaaaaaa
	s_cmp_lt_u32 s8, 0x55555555
	s_cselect_b32 s13, 2, 0
	v_cndmask_b32_e64 v0, 0, 1, s[26:27]
	s_andn2_b64 vcc, exec, s[6:7]
	v_cmp_ne_u32_e64 s[6:7], 1, v0
	s_cbranch_vccz .LBB0_866

.LBB0_1151:
	v_mov_b64_e32 v[2:3], 0x200
	s_ashr_i32 s13, s12, 31
	v_cmp_lt_i64_e32 vcc, s[14:15], v[2:3]
	s_lshl_b64 s[14:15], s[12:13], 19
	s_add_u32 s14, s80, s14
	s_addc_u32 s15, s83, s15
	s_and_b64 s[16:17], vcc, exec
	s_cselect_b32 s13, s15, s7
	s_cselect_b32 s54, s14, s6
	s_ashr_i32 s11, s10, 31
	s_lshl_b64 s[16:17], s[10:11], 19
	s_add_u32 s16, s23, s16
	s_addc_u32 s17, s36, s17
	s_and_b64 s[26:27], vcc, exec
	s_cselect_b32 s11, s17, s9
	s_cselect_b32 s55, s16, s8
	s_add_u32 s6, s6, 0x40080
	s_addc_u32 s7, s7, 0
	s_add_u32 s56, s8, 0x100
	s_addc_u32 s57, s9, 0
	s_mov_b32 s58, -2
	s_add_u32 s8, s6, 0xfffc0080
	s_addc_u32 s9, s7, -1
	s_add_i32 s59, 0, 0x10000
	v_add_u32_e32 v0, s59, v249
	ds_read_b128 v[2:5], v0
	ds_read_b128 v[6:9], v0 offset:1024
	ds_read_b128 v[10:13], v0 offset:2048
	ds_read_b128 v[14:17], v0 offset:3072
	s_cmp_eq_u32 s58, 12
	s_cselect_b32 s27, s13, s9
	s_cselect_b32 s26, s54, s8
	s_cselect_b32 s9, s11, s57
	s_cselect_b32 s8, s55, s56
	v_lshl_add_u64 v[50:51], s[6:7], 0, v[234:235]
	s_add_i32 m0, s38, 0xc000
	ds_read_b128 v[18:21], v222
	ds_read_b128 v[22:25], v222 offset:1024
	ds_read_b128 v[26:29], v222 offset:2048
	ds_read_b128 v[30:33], v222 offset:3072
	ds_read_b128 v[34:37], v222 offset:4096
	ds_read_b128 v[38:41], v222 offset:5120
	ds_read_b128 v[42:45], v222 offset:6144
	ds_read_b128 v[46:49], v222 offset:7168
	global_load_lds_dwordx4 v[50:51], off
	v_lshl_add_u64 v[50:51], s[6:7], 0, v[236:237]
	s_add_i32 m0, s38, 0xe000
	s_nop 0
	global_load_lds_dwordx4 v[50:51], off
	s_waitcnt lgkmcnt(8)
	s_barrier
	s_waitcnt lgkmcnt(0)
	s_setprio 1
	s_waitcnt lgkmcnt(0)
	v_mfma_f32_16x16x32_bf16 v[150:153], v[10:13], v[42:45], 0
	v_mfma_f32_16x16x32_bf16 v[50:53], v[2:5], v[18:21], 0
	v_mfma_f32_16x16x32_bf16 v[54:57], v[10:13], v[18:21], 0
	v_mfma_f32_16x16x32_bf16 v[58:61], v[2:5], v[26:29], 0
	v_mfma_f32_16x16x32_bf16 v[62:65], v[10:13], v[26:29], 0
	v_mfma_f32_16x16x32_bf16 v[66:69], v[2:5], v[34:37], 0
	v_mfma_f32_16x16x32_bf16 v[70:73], v[10:13], v[34:37], 0
	v_mfma_f32_16x16x32_bf16 v[74:77], v[2:5], v[42:45], 0
	v_mfma_f32_16x16x32_bf16 v[150:153], v[14:17], v[46:49], v[150:153]
	v_mfma_f32_16x16x32_bf16 v[50:53], v[6:9], v[22:25], v[50:53]
	v_mfma_f32_16x16x32_bf16 v[54:57], v[14:17], v[22:25], v[54:57]
	v_mfma_f32_16x16x32_bf16 v[58:61], v[6:9], v[30:33], v[58:61]
	v_mfma_f32_16x16x32_bf16 v[62:65], v[14:17], v[30:33], v[62:65]
	v_mfma_f32_16x16x32_bf16 v[66:69], v[6:9], v[38:41], v[66:69]
	v_mfma_f32_16x16x32_bf16 v[70:73], v[14:17], v[38:41], v[70:73]
	v_mfma_f32_16x16x32_bf16 v[74:77], v[6:9], v[46:49], v[74:77]
	s_setprio 0
	s_barrier
	s_add_i32 s64, 0, 0x14000
	s_add_i32 s59, s59, s37
	v_add_u32_e32 v0, s64, v249
	v_lshl_add_u64 v[238:239], s[8:9], 0, v[230:231]
	s_mov_b32 m0, s59
	ds_read_b128 v[154:157], v0
	ds_read_b128 v[166:169], v0 offset:1024
	ds_read_b128 v[170:173], v0 offset:2048
	ds_read_b128 v[182:185], v0 offset:3072
	global_load_lds_dwordx4 v[238:239], off
	v_lshl_add_u64 v[240:241], s[8:9], 0, v[226:227]
	s_add_i32 m0, s59, 0x2000
	s_nop 0
	global_load_lds_dwordx4 v[240:241], off
	s_barrier
	s_waitcnt lgkmcnt(0)
	s_setprio 1
	s_waitcnt lgkmcnt(0)
	v_mfma_f32_16x16x32_bf16 v[186:189], v[154:157], v[18:21], 0
	v_mfma_f32_16x16x32_bf16 v[18:21], v[170:173], v[18:21], 0
	v_mfma_f32_16x16x32_bf16 v[194:197], v[166:169], v[22:25], v[186:189]
	v_mfma_f32_16x16x32_bf16 v[18:21], v[182:185], v[22:25], v[18:21]
	v_mfma_f32_16x16x32_bf16 v[22:25], v[154:157], v[26:29], 0
	v_mfma_f32_16x16x32_bf16 v[26:29], v[170:173], v[26:29], 0
	v_mfma_f32_16x16x32_bf16 v[22:25], v[166:169], v[30:33], v[22:25]
	v_mfma_f32_16x16x32_bf16 v[26:29], v[182:185], v[30:33], v[26:29]
	v_mfma_f32_16x16x32_bf16 v[30:33], v[154:157], v[34:37], 0
	v_mfma_f32_16x16x32_bf16 v[34:37], v[170:173], v[34:37], 0
	v_mfma_f32_16x16x32_bf16 v[30:33], v[166:169], v[38:41], v[30:33]
	v_mfma_f32_16x16x32_bf16 v[34:37], v[182:185], v[38:41], v[34:37]
	v_mfma_f32_16x16x32_bf16 v[38:41], v[154:157], v[42:45], 0
	v_mfma_f32_16x16x32_bf16 v[42:45], v[170:173], v[42:45], 0
	v_mfma_f32_16x16x32_bf16 v[38:41], v[166:169], v[46:49], v[38:41]
	v_mfma_f32_16x16x32_bf16 v[42:45], v[182:185], v[46:49], v[42:45]
	s_setprio 0
	s_mov_b32 m0, s38
	v_lshl_add_u64 v[242:243], s[26:27], 0, v[232:233]
	s_barrier
	ds_read_b128 v[46:49], v222 offset:16384
	ds_read_b128 v[142:145], v222 offset:17408
	ds_read_b128 v[146:149], v222 offset:18432
	ds_read_b128 v[158:161], v222 offset:19456
	ds_read_b128 v[162:165], v222 offset:20480
	ds_read_b128 v[174:177], v222 offset:21504
	ds_read_b128 v[178:181], v222 offset:22528
	ds_read_b128 v[186:189], v222 offset:23552
	global_load_lds_dwordx4 v[242:243], off
	v_lshl_add_u64 v[224:225], s[26:27], 0, v[228:229]
	s_mov_b32 m0, s39
	s_nop 0
	global_load_lds_dwordx4 v[224:225], off
	s_barrier
	s_waitcnt lgkmcnt(0)
	s_setprio 1
	s_waitcnt lgkmcnt(0)
	v_mfma_f32_16x16x32_bf16 v[138:141], v[2:5], v[46:49], 0
	v_mfma_f32_16x16x32_bf16 v[134:137], v[10:13], v[46:49], 0
	v_mfma_f32_16x16x32_bf16 v[122:125], v[2:5], v[146:149], 0
	v_mfma_f32_16x16x32_bf16 v[118:121], v[10:13], v[146:149], 0
	v_mfma_f32_16x16x32_bf16 v[106:109], v[2:5], v[162:165], 0
	v_mfma_f32_16x16x32_bf16 v[102:105], v[10:13], v[162:165], 0
	v_mfma_f32_16x16x32_bf16 v[2:5], v[2:5], v[178:181], 0
	v_mfma_f32_16x16x32_bf16 v[138:141], v[6:9], v[142:145], v[138:141]
	v_mfma_f32_16x16x32_bf16 v[134:137], v[14:17], v[142:145], v[134:137]
	v_mfma_f32_16x16x32_bf16 v[122:125], v[6:9], v[158:161], v[122:125]
	v_mfma_f32_16x16x32_bf16 v[118:121], v[14:17], v[158:161], v[118:121]
	v_mfma_f32_16x16x32_bf16 v[106:109], v[6:9], v[174:177], v[106:109]
	v_mfma_f32_16x16x32_bf16 v[102:105], v[14:17], v[174:177], v[102:105]
	v_mfma_f32_16x16x32_bf16 v[2:5], v[6:9], v[186:189], v[2:5]
	v_mfma_f32_16x16x32_bf16 v[6:9], v[10:13], v[178:181], 0
	v_mfma_f32_16x16x32_bf16 v[6:9], v[14:17], v[186:189], v[6:9]
	s_setprio 0
	s_barrier
	s_add_u32 s62, s8, 0x40000
	s_addc_u32 s63, s9, 0
	s_add_i32 s59, s64, s37
	v_lshl_add_u64 v[10:11], s[62:63], 0, v[230:231]
	s_mov_b32 m0, s59
	s_nop 0
	global_load_lds_dwordx4 v[10:11], off
	v_lshl_add_u64 v[10:11], s[62:63], 0, v[226:227]
	s_add_i32 m0, s59, 0x2000
	s_nop 0
	global_load_lds_dwordx4 v[10:11], off
	s_waitcnt vmcnt(6)
	s_barrier
	s_setprio 1
	v_mfma_f32_16x16x32_bf16 v[86:89], v[170:173], v[146:149], 0
	v_mfma_f32_16x16x32_bf16 v[110:113], v[182:185], v[158:161], v[86:89]
	v_mfma_f32_16x16x32_bf16 v[86:89], v[154:157], v[162:165], 0
	v_mfma_f32_16x16x32_bf16 v[98:101], v[166:169], v[174:177], v[86:89]
	v_mfma_f32_16x16x32_bf16 v[86:89], v[170:173], v[162:165], 0
	v_mfma_f32_16x16x32_bf16 v[82:85], v[154:157], v[178:181], 0
	v_mfma_f32_16x16x32_bf16 v[78:81], v[170:173], v[178:181], 0
	v_mfma_f32_16x16x32_bf16 v[10:13], v[154:157], v[46:49], 0
	v_mfma_f32_16x16x32_bf16 v[14:17], v[170:173], v[46:49], 0
	v_mfma_f32_16x16x32_bf16 v[46:49], v[154:157], v[146:149], 0
	v_mfma_f32_16x16x32_bf16 v[94:97], v[182:185], v[174:177], v[86:89]
	v_mfma_f32_16x16x32_bf16 v[82:85], v[166:169], v[186:189], v[82:85]
	v_mfma_f32_16x16x32_bf16 v[78:81], v[182:185], v[186:189], v[78:81]
	v_mfma_f32_16x16x32_bf16 v[10:13], v[166:169], v[142:145], v[10:13]
	v_mfma_f32_16x16x32_bf16 v[14:17], v[182:185], v[142:145], v[14:17]
	v_mfma_f32_16x16x32_bf16 v[46:49], v[166:169], v[158:161], v[46:49]
	s_setprio 0
	s_add_i32 s59, 0, 0x18000
	v_add_u32_e32 v0, s59, v249
	s_barrier
	ds_read_b128 v[86:89], v0
	ds_read_b128 v[90:93], v0 offset:1024
	ds_read_b128 v[114:117], v0 offset:2048
	ds_read_b128 v[126:129], v0 offset:3072
	s_add_u32 s26, s26, 0x40000
	s_addc_u32 s27, s27, 0
	s_mov_b32 m0, s40
	v_lshl_add_u64 v[154:155], s[26:27], 0, v[232:233]
	ds_read_b128 v[130:133], v222 offset:32768
	ds_read_b128 v[142:145], v222 offset:33792
	ds_read_b128 v[146:149], v222 offset:34816
	ds_read_b128 v[158:161], v222 offset:35840
	ds_read_b128 v[206:209], v222 offset:36864
	ds_read_b128 v[210:213], v222 offset:37888
	ds_read_b128 v[214:217], v222 offset:38912
	ds_read_b128 v[218:221], v222 offset:39936
	global_load_lds_dwordx4 v[154:155], off
	v_lshl_add_u64 v[154:155], s[26:27], 0, v[228:229]
	s_mov_b32 m0, s41
	s_nop 0
	global_load_lds_dwordx4 v[154:155], off
	s_waitcnt lgkmcnt(8)
	s_barrier
	s_waitcnt lgkmcnt(0)
	s_setprio 1
	s_waitcnt lgkmcnt(0)
	v_mfma_f32_16x16x32_bf16 v[50:53], v[86:89], v[130:133], v[50:53]
	v_mfma_f32_16x16x32_bf16 v[202:205], v[90:93], v[142:145], v[50:53]
	v_mfma_f32_16x16x32_bf16 v[50:53], v[114:117], v[130:133], v[54:57]
	v_mfma_f32_16x16x32_bf16 v[198:201], v[126:129], v[142:145], v[50:53]
	v_mfma_f32_16x16x32_bf16 v[50:53], v[86:89], v[146:149], v[58:61]
	v_mfma_f32_16x16x32_bf16 v[186:189], v[90:93], v[158:161], v[50:53]
	v_mfma_f32_16x16x32_bf16 v[50:53], v[114:117], v[146:149], v[62:65]
	v_mfma_f32_16x16x32_bf16 v[182:185], v[126:129], v[158:161], v[50:53]
	v_mfma_f32_16x16x32_bf16 v[50:53], v[86:89], v[206:209], v[66:69]
	v_mfma_f32_16x16x32_bf16 v[170:173], v[90:93], v[210:213], v[50:53]
	v_mfma_f32_16x16x32_bf16 v[50:53], v[114:117], v[206:209], v[70:73]
	v_mfma_f32_16x16x32_bf16 v[166:169], v[126:129], v[210:213], v[50:53]
	v_mfma_f32_16x16x32_bf16 v[50:53], v[86:89], v[214:217], v[74:77]
	v_mfma_f32_16x16x32_bf16 v[154:157], v[90:93], v[218:221], v[50:53]
	v_mfma_f32_16x16x32_bf16 v[50:53], v[114:117], v[214:217], v[150:153]
	v_mfma_f32_16x16x32_bf16 v[150:153], v[126:129], v[218:221], v[50:53]
	s_setprio 0
	s_barrier
	s_add_i32 s26, 0, 0x1c000
	s_add_i32 s27, s59, s37
	v_add_u32_e32 v0, s26, v249
	v_lshl_add_u64 v[66:67], v[238:239], 0, s[20:21]
	s_mov_b32 m0, s27
	ds_read_b128 v[50:53], v0
	ds_read_b128 v[54:57], v0 offset:1024
	ds_read_b128 v[58:61], v0 offset:2048
	ds_read_b128 v[62:65], v0 offset:3072
	global_load_lds_dwordx4 v[66:67], off
	v_lshl_add_u64 v[66:67], v[240:241], 0, s[20:21]
	s_add_i32 m0, s27, 0x2000
	s_nop 0
	global_load_lds_dwordx4 v[66:67], off
	s_barrier
	s_waitcnt lgkmcnt(0)
	s_setprio 1
	s_waitcnt lgkmcnt(0)
	v_mfma_f32_16x16x32_bf16 v[18:21], v[58:61], v[130:133], v[18:21]
	v_mfma_f32_16x16x32_bf16 v[190:193], v[62:65], v[142:145], v[18:21]
	v_mfma_f32_16x16x32_bf16 v[18:21], v[50:53], v[146:149], v[22:25]
	v_mfma_f32_16x16x32_bf16 v[178:181], v[54:57], v[158:161], v[18:21]
	v_mfma_f32_16x16x32_bf16 v[18:21], v[58:61], v[146:149], v[26:29]
	v_mfma_f32_16x16x32_bf16 v[174:177], v[62:65], v[158:161], v[18:21]
	v_mfma_f32_16x16x32_bf16 v[18:21], v[50:53], v[206:209], v[30:33]
	v_mfma_f32_16x16x32_bf16 v[162:165], v[54:57], v[210:213], v[18:21]
	v_mfma_f32_16x16x32_bf16 v[18:21], v[58:61], v[206:209], v[34:37]
	v_mfma_f32_16x16x32_bf16 v[158:161], v[62:65], v[210:213], v[18:21]
	v_mfma_f32_16x16x32_bf16 v[18:21], v[50:53], v[214:217], v[38:41]
	v_mfma_f32_16x16x32_bf16 v[66:69], v[50:53], v[130:133], v[194:197]
	v_mfma_f32_16x16x32_bf16 v[146:149], v[54:57], v[218:221], v[18:21]
	v_mfma_f32_16x16x32_bf16 v[18:21], v[58:61], v[214:217], v[42:45]
	v_mfma_f32_16x16x32_bf16 v[194:197], v[54:57], v[142:145], v[66:69]
	v_mfma_f32_16x16x32_bf16 v[142:145], v[62:65], v[218:221], v[18:21]
	s_setprio 0
	s_mov_b32 m0, s44
	v_lshl_add_u64 v[70:71], v[242:243], 0, s[20:21]
	s_barrier
	s_nop 1
	ds_read_b128 v[18:21], v222 offset:49152
	ds_read_b128 v[22:25], v222 offset:50176
	ds_read_b128 v[26:29], v222 offset:51200
	ds_read_b128 v[30:33], v222 offset:52224
	ds_read_b128 v[34:37], v222 offset:53248
	ds_read_b128 v[38:41], v222 offset:54272
	ds_read_b128 v[42:45], v222 offset:55296
	ds_read_b128 v[66:69], v222 offset:56320
	global_load_lds_dwordx4 v[70:71], off
	v_lshl_add_u64 v[70:71], v[224:225], 0, s[20:21]
	s_mov_b32 m0, s45
	s_nop 0
	global_load_lds_dwordx4 v[70:71], off
	s_barrier
	s_waitcnt lgkmcnt(0)
	s_setprio 1
	s_waitcnt lgkmcnt(0)
	v_mfma_f32_16x16x32_bf16 v[70:73], v[86:89], v[18:21], v[138:141]
	v_mfma_f32_16x16x32_bf16 v[138:141], v[90:93], v[22:25], v[70:73]
	v_mfma_f32_16x16x32_bf16 v[70:73], v[114:117], v[18:21], v[134:137]
	v_mfma_f32_16x16x32_bf16 v[134:137], v[126:129], v[22:25], v[70:73]
	v_mfma_f32_16x16x32_bf16 v[70:73], v[86:89], v[26:29], v[122:125]
	v_mfma_f32_16x16x32_bf16 v[122:125], v[90:93], v[30:33], v[70:73]
	v_mfma_f32_16x16x32_bf16 v[70:73], v[114:117], v[26:29], v[118:121]
	v_mfma_f32_16x16x32_bf16 v[118:121], v[126:129], v[30:33], v[70:73]
	v_mfma_f32_16x16x32_bf16 v[70:73], v[86:89], v[34:37], v[106:109]
	v_mfma_f32_16x16x32_bf16 v[2:5], v[86:89], v[42:45], v[2:5]
	v_mfma_f32_16x16x32_bf16 v[106:109], v[90:93], v[38:41], v[70:73]
	v_mfma_f32_16x16x32_bf16 v[70:73], v[114:117], v[34:37], v[102:105]
	v_mfma_f32_16x16x32_bf16 v[90:93], v[90:93], v[66:69], v[2:5]
	v_mfma_f32_16x16x32_bf16 v[2:5], v[114:117], v[42:45], v[6:9]
	v_mfma_f32_16x16x32_bf16 v[102:105], v[126:129], v[38:41], v[70:73]
	v_mfma_f32_16x16x32_bf16 v[86:89], v[126:129], v[66:69], v[2:5]
	s_setprio 0
	s_barrier
	s_add_u32 s8, s8, 0x40080
	s_addc_u32 s9, s9, 0
	s_add_i32 s26, s26, s37
	s_nop 0
	v_lshl_add_u64 v[2:3], s[8:9], 0, v[230:231]
	s_mov_b32 m0, s26
	s_nop 0
	global_load_lds_dwordx4 v[2:3], off
	v_lshl_add_u64 v[2:3], s[8:9], 0, v[226:227]
	s_add_i32 m0, s26, 0x2000
	s_nop 0
	global_load_lds_dwordx4 v[2:3], off
	s_waitcnt vmcnt(6)
	s_barrier
	s_setprio 1
	v_mfma_f32_16x16x32_bf16 v[2:5], v[50:53], v[18:21], v[10:13]
	v_mfma_f32_16x16x32_bf16 v[130:133], v[54:57], v[22:25], v[2:5]
	v_mfma_f32_16x16x32_bf16 v[2:5], v[58:61], v[18:21], v[14:17]
	v_mfma_f32_16x16x32_bf16 v[126:129], v[62:65], v[22:25], v[2:5]
	v_mfma_f32_16x16x32_bf16 v[2:5], v[50:53], v[26:29], v[46:49]
	v_mfma_f32_16x16x32_bf16 v[114:117], v[54:57], v[30:33], v[2:5]
	v_mfma_f32_16x16x32_bf16 v[2:5], v[58:61], v[26:29], v[110:113]
	v_mfma_f32_16x16x32_bf16 v[110:113], v[62:65], v[30:33], v[2:5]
	v_mfma_f32_16x16x32_bf16 v[2:5], v[50:53], v[34:37], v[98:101]
	v_mfma_f32_16x16x32_bf16 v[98:101], v[54:57], v[38:41], v[2:5]
	v_mfma_f32_16x16x32_bf16 v[2:5], v[58:61], v[34:37], v[94:97]
	v_mfma_f32_16x16x32_bf16 v[94:97], v[62:65], v[38:41], v[2:5]
	v_mfma_f32_16x16x32_bf16 v[2:5], v[50:53], v[42:45], v[82:85]
	v_mfma_f32_16x16x32_bf16 v[82:85], v[54:57], v[66:69], v[2:5]
	v_mfma_f32_16x16x32_bf16 v[2:5], v[58:61], v[42:45], v[78:81]
	v_mfma_f32_16x16x32_bf16 v[78:81], v[62:65], v[66:69], v[2:5]
	s_setprio 0
	s_add_i32 s58, s58, 2
	s_add_u32 s6, s6, 0x100
	s_addc_u32 s7, s7, 0
	s_add_u32 s56, s56, 0x100
	s_addc_u32 s57, s57, 0
	s_cmp_gt_u32 s58, 13
	s_barrier
	s_cbranch_scc0 .LBB0_1152
	s_branch .Lpeel_exit_g3

.Lpeel_exit_g3:
	s_lshr_b32 s11, s52, 31
	s_cmp_lg_u32 s11, 0
	s_cselect_b64 s[6:7], -1, 0
	s_cmp_eq_u32 s11, 0
	s_cselect_b64 s[8:9], -1, 0
	s_and_b64 vcc, s[8:9], exec
	s_cselect_b32 s8, 0, s48
	v_or_b32_e32 v0, s8, v246
	s_cselect_b32 s9, s35, s68
	s_cselect_b32 s8, s34, s33
	v_lshlrev_b32_e32 v0, 2, v0
	v_lshl_add_u64 v[240:241], s[8:9], 0, v[0:1]
	s_cselect_b32 s9, s61, s70
	s_cselect_b32 s8, s60, s69
	v_mov_b32_e32 v18, 0
	v_lshl_add_u32 v238, s53, 8, v252
	v_lshl_add_u64 v[242:243], s[8:9], 0, v[0:1]
	v_mov_b32_e32 v19, v18
	v_mov_b32_e32 v20, v18
	v_mov_b32_e32 v21, v18
	s_cbranch_vccnz .LBB0_1155
	v_lshlrev_b32_e32 v0, 7, v238
	v_and_b32_e32 v0, 0x3e780, v0
	v_lshl_add_u64 v[2:3], v[240:241], 0, v[0:1]
	v_lshl_add_u64 v[4:5], v[242:243], 0, v[0:1]
	global_load_dwordx4 v[18:21], v[2:3], off
	global_load_dwordx4 v[218:221], v[4:5], off
